# p12 epilogue: issue all 16 x1 loads up front, drop 15 vmcnt(0) drains (on top of p10 epilogue)
# speedup vs baseline: 1.0188x; 1.0052x over previous
; __device__ __forceinline__ u32x4 packh44(const f32x4 a, const f32x4 b) { u32x4 w; w.x = pkh2(a[0], a[1]); w.y = pkh2(a[2], a[3]); w.z = pkh2(b[0], b[1]); w.w = pkh2(b[2], b[3]); return w; }
;     __device__ __forceinline__ bool operator()(f32x4 (&acc)[2][2][4][2], const Unit& u, int wr, int wc, int fr, int fq) const {
;         const float* gp0 = gate + (size_t)((u.pm * 256) >> 12) * 12288 + u.pn * 256 + wc * 32 + 8 * fq;
;         const f32x4 ga0 = *(const f32x4*)gp0, ga1 = *(const f32x4*)(gp0 + 4), gb0 = *(const f32x4*)(gp0 + 128), gb1 = *(const f32x4*)(gp0 + 132);
;         EPI_LOOP_BEGIN const int col = u.pn * 256 + cl; const size_t off = (size_t)row * DM + col;
;             const f32x4 g0 = bj ? gb0 : ga0, g1 = bj ? gb1 : ga1; f32x4 x0, x1; unpackh44(*(const u32x4*)(base + off), x0, x1);
;             *(u32x4*)(o + off) = packh44(x0 + g0 * v0, x1 + g1 * v1); EPI_LOOP_END
;         return false;
;     }
.LBB0_949:
	s_ashr_i32 s24, s52, 4
	s_mul_hi_i32 s25, s24, 0xc000
	s_mul_i32 s24, s24, 0xc000
	s_add_u32 s26, s43, s24
	s_addc_u32 s27, s44, s25
	s_lshl_b32 s24, s53, 8
	v_lshl_add_u32 v166, s52, 8, v155
	v_or_b32_e32 v162, s24, v169
	v_ashrrev_i32_e32 v167, 31, v166
	v_lshlrev_b64 v[164:165], 11, v[166:167]
	v_ashrrev_i32_e32 v163, 31, v162
	v_lshl_add_u64 v[122:123], v[164:165], 0, v[162:163]
	v_lshlrev_b64 v[122:123], 1, v[122:123]
	s_ashr_i32 s25, s24, 31
	s_nop 15
	s_nop 7
	v_lshl_add_u64 v[178:179], s[82:83], 0, v[122:123]
	s_lshl_b64 s[24:25], s[24:25], 2
	global_load_dwordx4 v[174:177], v[178:179], off
	global_load_dwordx4 v[188:191], v[178:179], off offset:256
	v_add_co_u32_e32 v232, vcc, 0x10000, v178
	s_nop 1
	v_addc_co_u32_e32 v233, vcc, 0, v179, vcc
	global_load_dwordx4 v[192:195], v[232:233], off
	global_load_dwordx4 v[196:199], v[232:233], off offset:256
	v_add_co_u32_e32 v232, vcc, 0x10000, v232
	s_nop 1
	v_addc_co_u32_e32 v233, vcc, 0, v233, vcc
	global_load_dwordx4 v[200:203], v[232:233], off
	global_load_dwordx4 v[204:207], v[232:233], off offset:256
	v_add_co_u32_e32 v232, vcc, 0x10000, v232
	s_nop 1
	v_addc_co_u32_e32 v233, vcc, 0, v233, vcc
	global_load_dwordx4 v[208:211], v[232:233], off
	global_load_dwordx4 v[212:215], v[232:233], off offset:256
	v_add_co_u32_e32 v232, vcc, 0x50000, v232
	s_nop 1
	v_addc_co_u32_e32 v233, vcc, 0, v233, vcc
	global_load_dwordx4 v[216:219], v[232:233], off
	global_load_dwordx4 v[220:223], v[232:233], off offset:256
	v_add_co_u32_e32 v232, vcc, 0x10000, v232
	s_nop 1
	v_addc_co_u32_e32 v233, vcc, 0, v233, vcc
	global_load_dwordx4 v[224:227], v[232:233], off
	global_load_dwordx4 v[228:231], v[232:233], off offset:256
	v_add_co_u32_e32 v232, vcc, 0x10000, v232
	s_nop 1
	v_addc_co_u32_e32 v233, vcc, 0, v233, vcc
	global_load_dwordx4 v[236:239], v[232:233], off
	global_load_dwordx4 v[240:243], v[232:233], off offset:256
	v_add_co_u32_e32 v232, vcc, 0x10000, v232
	s_nop 1
	v_addc_co_u32_e32 v233, vcc, 0, v233, vcc
	global_load_dwordx4 v[244:247], v[232:233], off
	global_load_dwordx4 v[248:251], v[232:233], off offset:256
	s_add_u32 s24, s26, s24
	s_addc_u32 s25, s27, s25
	s_add_u32 s24, s24, s50
	s_addc_u32 s25, s25, 0
	global_load_dwordx4 v[134:137], v173, s[24:25]
	global_load_dwordx4 v[130:133], v173, s[24:25] offset:16
	v_lshl_add_u64 v[180:181], s[8:9], 0, v[122:123]
	global_load_dwordx4 v[122:125], v173, s[24:25] offset:528
	global_load_dwordx4 v[126:129], v173, s[24:25] offset:512
	s_and_b64 vcc, exec, s[0:1]
	s_mov_b64 s[0:1], -1
	s_waitcnt vmcnt(0)
	v_cvt_f32_f16_e32 v182, v174
	v_cvt_f32_f16_sdwa v183, v174 dst_sel:DWORD dst_unused:UNUSED_PAD src0_sel:WORD_1
	v_cvt_f32_f16_e32 v174, v175
	v_cvt_f32_f16_sdwa v175, v175 dst_sel:DWORD dst_unused:UNUSED_PAD src0_sel:WORD_1
	v_cvt_f32_f16_e32 v184, v176
	v_cvt_f32_f16_e32 v186, v177
	v_cvt_f32_f16_sdwa v187, v177 dst_sel:DWORD dst_unused:UNUSED_PAD src0_sel:WORD_1
	v_cvt_f32_f16_sdwa v185, v176 dst_sel:DWORD dst_unused:UNUSED_PAD src0_sel:WORD_1
	v_pk_fma_f32 v[144:145], v[144:145], v[136:137], v[174:175]
	v_pk_fma_f32 v[142:143], v[142:143], v[134:135], v[182:183]
	v_pk_fma_f32 v[174:175], v[140:141], v[132:133], v[186:187]
	v_pk_fma_f32 v[140:141], v[138:139], v[130:131], v[184:185]
	v_cvt_pk_f16_f32 v138, v142, v143
	v_cvt_pk_f16_f32 v139, v144, v145
	v_cvt_pk_f16_f32 v140, v140, v141
	v_cvt_pk_f16_f32 v141, v174, v175
	global_store_dwordx4 v[180:181], v[138:141], off
	s_nop 0
	s_nop 0
	v_cvt_f32_f16_e32 v180, v188
	v_or_b32_e32 v138, 16, v166
	v_cvt_f32_f16_sdwa v181, v188 dst_sel:DWORD dst_unused:UNUSED_PAD src0_sel:WORD_1
	v_cvt_f32_f16_e32 v140, v189
	v_cvt_f32_f16_sdwa v141, v189 dst_sel:DWORD dst_unused:UNUSED_PAD src0_sel:WORD_1
	v_cvt_f32_f16_e32 v182, v190
	v_cvt_f32_f16_e32 v184, v191
	v_cvt_f32_f16_sdwa v185, v191 dst_sel:DWORD dst_unused:UNUSED_PAD src0_sel:WORD_1
	v_cvt_f32_f16_sdwa v183, v190 dst_sel:DWORD dst_unused:UNUSED_PAD src0_sel:WORD_1
	v_ashrrev_i32_e32 v139, 31, v138
	v_lshlrev_b64 v[144:145], 11, v[138:139]
	v_or_b32_e32 v138, 0x80, v162
	v_ashrrev_i32_e32 v139, 31, v138
	v_lshl_add_u64 v[174:175], v[144:145], 0, v[162:163]
	v_lshl_add_u64 v[176:177], v[164:165], 0, v[138:139]
	v_pk_fma_f32 v[120:121], v[120:121], v[128:129], v[140:141]
	v_pk_fma_f32 v[118:119], v[118:119], v[126:127], v[180:181]
	v_pk_fma_f32 v[140:141], v[116:117], v[124:125], v[184:185]
	v_pk_fma_f32 v[116:117], v[114:115], v[122:123], v[182:183]
	v_lshlrev_b64 v[174:175], 1, v[174:175]
	v_lshl_add_u64 v[176:177], v[176:177], 1, s[8:9]
	v_cvt_pk_f16_f32 v114, v118, v119
	v_cvt_pk_f16_f32 v115, v120, v121
	v_cvt_pk_f16_f32 v116, v116, v117
	v_cvt_pk_f16_f32 v117, v140, v141
	v_lshl_add_u64 v[178:179], s[82:83], 0, v[174:175]
	global_store_dwordx4 v[176:177], v[114:117], off
	s_nop 0
	v_lshl_add_u64 v[118:119], s[8:9], 0, v[174:175]
	s_nop 0
	v_cvt_f32_f16_e32 v120, v192
	v_cvt_f32_f16_sdwa v121, v192 dst_sel:DWORD dst_unused:UNUSED_PAD src0_sel:WORD_1
	v_cvt_f32_f16_e32 v114, v193
	v_cvt_f32_f16_sdwa v115, v193 dst_sel:DWORD dst_unused:UNUSED_PAD src0_sel:WORD_1
	v_cvt_f32_f16_e32 v140, v194
	v_cvt_f32_f16_e32 v142, v195
	v_cvt_f32_f16_sdwa v143, v195 dst_sel:DWORD dst_unused:UNUSED_PAD src0_sel:WORD_1
	v_cvt_f32_f16_sdwa v141, v194 dst_sel:DWORD dst_unused:UNUSED_PAD src0_sel:WORD_1
	v_pk_fma_f32 v[112:113], v[112:113], v[136:137], v[114:115]
	v_pk_fma_f32 v[110:111], v[110:111], v[134:135], v[120:121]
	v_pk_fma_f32 v[114:115], v[108:109], v[132:133], v[142:143]
	v_pk_fma_f32 v[108:109], v[106:107], v[130:131], v[140:141]
	v_cvt_pk_f16_f32 v106, v110, v111
	v_cvt_pk_f16_f32 v107, v112, v113
	v_cvt_pk_f16_f32 v108, v108, v109
; __device__ __forceinline__ u32x4 packh44(const f32x4 a, const f32x4 b) { u32x4 w; w.x = pkh2(a[0], a[1]); w.y = pkh2(a[2], a[3]); w.z = pkh2(b[0], b[1]); w.w = pkh2(b[2], b[3]); return w; }
;     __device__ __forceinline__ bool operator()(f32x4 (&acc)[2][2][4][2], const Unit& u, int wr, int wc, int fr, int fq) const {
;     ...
;         EPI_LOOP_BEGIN const int col = u.pn * 256 + cl; const size_t off = (size_t)row * DM + col;
;             const f32x4 g0 = bj ? gb0 : ga0, g1 = bj ? gb1 : ga1; f32x4 x0, x1; unpackh44(*(const u32x4*)(base + off), x0, x1);
;             *(u32x4*)(o + off) = packh44(x0 + g0 * v0, x1 + g1 * v1); EPI_LOOP_END
	v_cvt_pk_f16_f32 v109, v114, v115
	global_store_dwordx4 v[118:119], v[106:109], off
	s_nop 0
	v_or_b32_e32 v110, 32, v166
	v_ashrrev_i32_e32 v111, 31, v110
	v_lshlrev_b64 v[110:111], 11, v[110:111]
	v_lshl_add_u64 v[112:113], v[110:111], 0, v[162:163]
	v_lshl_add_u64 v[114:115], v[144:145], 0, v[138:139]
	v_lshlrev_b64 v[112:113], 1, v[112:113]
	v_lshl_add_u64 v[114:115], v[114:115], 1, s[8:9]
	v_lshl_add_u64 v[116:117], s[82:83], 0, v[112:113]
	s_nop 0
	v_cvt_f32_f16_e32 v118, v196
	v_cvt_f32_f16_sdwa v119, v196 dst_sel:DWORD dst_unused:UNUSED_PAD src0_sel:WORD_1
	v_cvt_f32_f16_e32 v106, v197
	v_cvt_f32_f16_sdwa v107, v197 dst_sel:DWORD dst_unused:UNUSED_PAD src0_sel:WORD_1
	v_cvt_f32_f16_e32 v120, v198
	v_cvt_f32_f16_e32 v140, v199
	v_cvt_f32_f16_sdwa v141, v199 dst_sel:DWORD dst_unused:UNUSED_PAD src0_sel:WORD_1
	v_cvt_f32_f16_sdwa v121, v198 dst_sel:DWORD dst_unused:UNUSED_PAD src0_sel:WORD_1
	v_pk_fma_f32 v[104:105], v[104:105], v[128:129], v[106:107]
	v_pk_fma_f32 v[102:103], v[102:103], v[126:127], v[118:119]
	v_pk_fma_f32 v[106:107], v[100:101], v[124:125], v[140:141]
	v_pk_fma_f32 v[100:101], v[98:99], v[122:123], v[120:121]
	v_cvt_pk_f16_f32 v98, v102, v103
	v_cvt_pk_f16_f32 v99, v104, v105
	v_cvt_pk_f16_f32 v100, v100, v101
	v_cvt_pk_f16_f32 v101, v106, v107
	global_store_dwordx4 v[114:115], v[98:101], off
	s_nop 0
	v_lshl_add_u64 v[102:103], s[8:9], 0, v[112:113]
	s_nop 0
	v_cvt_f32_f16_e32 v104, v200
	v_cvt_f32_f16_sdwa v105, v200 dst_sel:DWORD dst_unused:UNUSED_PAD src0_sel:WORD_1
	v_cvt_f32_f16_e32 v98, v201
	v_cvt_f32_f16_sdwa v99, v201 dst_sel:DWORD dst_unused:UNUSED_PAD src0_sel:WORD_1
	v_cvt_f32_f16_e32 v106, v202
	v_cvt_f32_f16_e32 v108, v203
	v_cvt_f32_f16_sdwa v109, v203 dst_sel:DWORD dst_unused:UNUSED_PAD src0_sel:WORD_1
	v_cvt_f32_f16_sdwa v107, v202 dst_sel:DWORD dst_unused:UNUSED_PAD src0_sel:WORD_1
	v_pk_fma_f32 v[96:97], v[96:97], v[136:137], v[98:99]
	v_pk_fma_f32 v[94:95], v[94:95], v[134:135], v[104:105]
	v_pk_fma_f32 v[98:99], v[92:93], v[132:133], v[108:109]
	v_pk_fma_f32 v[92:93], v[90:91], v[130:131], v[106:107]
	v_cvt_pk_f16_f32 v90, v94, v95
	v_cvt_pk_f16_f32 v91, v96, v97
	v_cvt_pk_f16_f32 v92, v92, v93
	v_cvt_pk_f16_f32 v93, v98, v99
	global_store_dwordx4 v[102:103], v[90:93], off
	s_nop 0
	v_or_b32_e32 v94, 48, v166
	v_ashrrev_i32_e32 v95, 31, v94
	v_lshlrev_b64 v[94:95], 11, v[94:95]
	v_lshl_add_u64 v[96:97], v[94:95], 0, v[162:163]
	v_lshl_add_u64 v[98:99], v[110:111], 0, v[138:139]
	v_lshlrev_b64 v[96:97], 1, v[96:97]
	v_lshl_add_u64 v[98:99], v[98:99], 1, s[8:9]
	v_lshl_add_u64 v[100:101], s[82:83], 0, v[96:97]
	s_nop 0
	v_cvt_f32_f16_e32 v102, v204
	v_cvt_f32_f16_sdwa v103, v204 dst_sel:DWORD dst_unused:UNUSED_PAD src0_sel:WORD_1
	v_cvt_f32_f16_e32 v90, v205
	v_cvt_f32_f16_sdwa v91, v205 dst_sel:DWORD dst_unused:UNUSED_PAD src0_sel:WORD_1
	v_cvt_f32_f16_e32 v104, v206
	v_cvt_f32_f16_e32 v106, v207
	v_cvt_f32_f16_sdwa v107, v207 dst_sel:DWORD dst_unused:UNUSED_PAD src0_sel:WORD_1
	v_cvt_f32_f16_sdwa v105, v206 dst_sel:DWORD dst_unused:UNUSED_PAD src0_sel:WORD_1
	v_pk_fma_f32 v[88:89], v[88:89], v[128:129], v[90:91]
	v_pk_fma_f32 v[86:87], v[86:87], v[126:127], v[102:103]
	v_pk_fma_f32 v[90:91], v[84:85], v[124:125], v[106:107]
	v_pk_fma_f32 v[84:85], v[82:83], v[122:123], v[104:105]
	v_cvt_pk_f16_f32 v82, v86, v87
	v_cvt_pk_f16_f32 v83, v88, v89
	v_cvt_pk_f16_f32 v84, v84, v85
	v_cvt_pk_f16_f32 v85, v90, v91
	global_store_dwordx4 v[98:99], v[82:85], off
	s_nop 0
	v_lshl_add_u64 v[86:87], s[8:9], 0, v[96:97]
	s_nop 0
	v_cvt_f32_f16_e32 v88, v208
	v_cvt_f32_f16_sdwa v89, v208 dst_sel:DWORD dst_unused:UNUSED_PAD src0_sel:WORD_1
	v_cvt_f32_f16_e32 v82, v209
	v_cvt_f32_f16_sdwa v83, v209 dst_sel:DWORD dst_unused:UNUSED_PAD src0_sel:WORD_1
	v_cvt_f32_f16_e32 v90, v210
	v_cvt_f32_f16_e32 v92, v211
	v_cvt_f32_f16_sdwa v93, v211 dst_sel:DWORD dst_unused:UNUSED_PAD src0_sel:WORD_1
	v_cvt_f32_f16_sdwa v91, v210 dst_sel:DWORD dst_unused:UNUSED_PAD src0_sel:WORD_1
	v_pk_fma_f32 v[80:81], v[80:81], v[136:137], v[82:83]
	v_pk_fma_f32 v[78:79], v[78:79], v[134:135], v[88:89]
	v_pk_fma_f32 v[82:83], v[76:77], v[132:133], v[92:93]
	v_pk_fma_f32 v[76:77], v[74:75], v[130:131], v[90:91]
	v_cvt_pk_f16_f32 v74, v78, v79
	v_cvt_pk_f16_f32 v75, v80, v81
	v_cvt_pk_f16_f32 v76, v76, v77
	v_cvt_pk_f16_f32 v77, v82, v83
	global_store_dwordx4 v[86:87], v[74:77], off
	s_nop 0
	v_lshl_add_u64 v[78:79], v[164:165], 0, s[14:15]
	v_lshl_add_u64 v[80:81], v[78:79], 0, v[162:163]
	v_lshl_add_u64 v[82:83], v[94:95], 0, v[138:139]
	v_lshlrev_b64 v[80:81], 1, v[80:81]
	v_lshl_add_u64 v[82:83], v[82:83], 1, s[8:9]
	v_lshl_add_u64 v[84:85], s[82:83], 0, v[80:81]
	s_nop 0
	v_cvt_f32_f16_e32 v86, v212
	v_cvt_f32_f16_sdwa v87, v212 dst_sel:DWORD dst_unused:UNUSED_PAD src0_sel:WORD_1
	v_cvt_f32_f16_e32 v74, v213
	v_cvt_f32_f16_sdwa v75, v213 dst_sel:DWORD dst_unused:UNUSED_PAD src0_sel:WORD_1
	v_cvt_f32_f16_e32 v88, v214
	v_cvt_f32_f16_e32 v90, v215
	v_cvt_f32_f16_sdwa v91, v215 dst_sel:DWORD dst_unused:UNUSED_PAD src0_sel:WORD_1
	v_cvt_f32_f16_sdwa v89, v214 dst_sel:DWORD dst_unused:UNUSED_PAD src0_sel:WORD_1
	v_pk_fma_f32 v[72:73], v[72:73], v[128:129], v[74:75]
	v_pk_fma_f32 v[70:71], v[70:71], v[126:127], v[86:87]
	v_pk_fma_f32 v[74:75], v[68:69], v[124:125], v[90:91]
	v_pk_fma_f32 v[68:69], v[66:67], v[122:123], v[88:89]
	v_cvt_pk_f16_f32 v66, v70, v71
	v_cvt_pk_f16_f32 v67, v72, v73
	v_cvt_pk_f16_f32 v68, v68, v69
	v_cvt_pk_f16_f32 v69, v74, v75
	global_store_dwordx4 v[82:83], v[66:69], off
	s_nop 0
	v_lshl_add_u64 v[70:71], s[8:9], 0, v[80:81]
	s_nop 0
	v_cvt_f32_f16_e32 v72, v216
	v_cvt_f32_f16_sdwa v73, v216 dst_sel:DWORD dst_unused:UNUSED_PAD src0_sel:WORD_1
; __device__ __forceinline__ u32x4 packh44(const f32x4 a, const f32x4 b) { u32x4 w; w.x = pkh2(a[0], a[1]); w.y = pkh2(a[2], a[3]); w.z = pkh2(b[0], b[1]); w.w = pkh2(b[2], b[3]); return w; }
;     __device__ __forceinline__ bool operator()(f32x4 (&acc)[2][2][4][2], const Unit& u, int wr, int wc, int fr, int fq) const {
;     ...
;         EPI_LOOP_BEGIN const int col = u.pn * 256 + cl; const size_t off = (size_t)row * DM + col;
;             const f32x4 g0 = bj ? gb0 : ga0, g1 = bj ? gb1 : ga1; f32x4 x0, x1; unpackh44(*(const u32x4*)(base + off), x0, x1);
;             *(u32x4*)(o + off) = packh44(x0 + g0 * v0, x1 + g1 * v1); EPI_LOOP_END
	v_cvt_f32_f16_e32 v66, v217
	v_cvt_f32_f16_sdwa v67, v217 dst_sel:DWORD dst_unused:UNUSED_PAD src0_sel:WORD_1
	v_cvt_f32_f16_e32 v74, v218
	v_cvt_f32_f16_e32 v76, v219
	v_cvt_f32_f16_sdwa v77, v219 dst_sel:DWORD dst_unused:UNUSED_PAD src0_sel:WORD_1
	v_cvt_f32_f16_sdwa v75, v218 dst_sel:DWORD dst_unused:UNUSED_PAD src0_sel:WORD_1
	v_pk_fma_f32 v[64:65], v[64:65], v[136:137], v[66:67]
	v_pk_fma_f32 v[62:63], v[62:63], v[134:135], v[72:73]
	v_pk_fma_f32 v[66:67], v[60:61], v[132:133], v[76:77]
	v_pk_fma_f32 v[60:61], v[58:59], v[130:131], v[74:75]
	v_cvt_pk_f16_f32 v58, v62, v63
	v_cvt_pk_f16_f32 v59, v64, v65
	v_cvt_pk_f16_f32 v60, v60, v61
	v_cvt_pk_f16_f32 v61, v66, v67
	global_store_dwordx4 v[70:71], v[58:61], off
	s_nop 0
	v_lshl_add_u64 v[62:63], v[164:165], 0, s[16:17]
	v_lshl_add_u64 v[64:65], v[62:63], 0, v[162:163]
	v_lshl_add_u64 v[66:67], v[78:79], 0, v[138:139]
	v_lshlrev_b64 v[64:65], 1, v[64:65]
	v_lshl_add_u64 v[66:67], v[66:67], 1, s[8:9]
	v_lshl_add_u64 v[68:69], s[82:83], 0, v[64:65]
	s_nop 0
	v_cvt_f32_f16_e32 v70, v220
	v_cvt_f32_f16_sdwa v71, v220 dst_sel:DWORD dst_unused:UNUSED_PAD src0_sel:WORD_1
	v_cvt_f32_f16_e32 v58, v221
	v_cvt_f32_f16_sdwa v59, v221 dst_sel:DWORD dst_unused:UNUSED_PAD src0_sel:WORD_1
	v_cvt_f32_f16_e32 v72, v222
	v_cvt_f32_f16_e32 v74, v223
	v_cvt_f32_f16_sdwa v75, v223 dst_sel:DWORD dst_unused:UNUSED_PAD src0_sel:WORD_1
	v_cvt_f32_f16_sdwa v73, v222 dst_sel:DWORD dst_unused:UNUSED_PAD src0_sel:WORD_1
	v_pk_fma_f32 v[56:57], v[56:57], v[128:129], v[58:59]
	v_pk_fma_f32 v[54:55], v[54:55], v[126:127], v[70:71]
	v_pk_fma_f32 v[58:59], v[52:53], v[124:125], v[74:75]
	v_pk_fma_f32 v[52:53], v[50:51], v[122:123], v[72:73]
	v_cvt_pk_f16_f32 v50, v54, v55
	v_cvt_pk_f16_f32 v51, v56, v57
	v_cvt_pk_f16_f32 v52, v52, v53
	v_cvt_pk_f16_f32 v53, v58, v59
	global_store_dwordx4 v[66:67], v[50:53], off
	s_nop 0
	v_lshl_add_u64 v[54:55], s[8:9], 0, v[64:65]
	s_nop 0
	v_cvt_f32_f16_e32 v56, v224
	v_cvt_f32_f16_sdwa v57, v224 dst_sel:DWORD dst_unused:UNUSED_PAD src0_sel:WORD_1
	v_cvt_f32_f16_e32 v50, v225
	v_cvt_f32_f16_sdwa v51, v225 dst_sel:DWORD dst_unused:UNUSED_PAD src0_sel:WORD_1
	v_cvt_f32_f16_e32 v58, v226
	v_cvt_f32_f16_e32 v60, v227
	v_cvt_f32_f16_sdwa v61, v227 dst_sel:DWORD dst_unused:UNUSED_PAD src0_sel:WORD_1
	v_cvt_f32_f16_sdwa v59, v226 dst_sel:DWORD dst_unused:UNUSED_PAD src0_sel:WORD_1
	v_pk_fma_f32 v[48:49], v[48:49], v[136:137], v[50:51]
	v_pk_fma_f32 v[46:47], v[46:47], v[134:135], v[56:57]
	v_pk_fma_f32 v[50:51], v[44:45], v[132:133], v[60:61]
	v_pk_fma_f32 v[44:45], v[42:43], v[130:131], v[58:59]
	v_cvt_pk_f16_f32 v42, v46, v47
	v_cvt_pk_f16_f32 v43, v48, v49
	v_cvt_pk_f16_f32 v44, v44, v45
	v_cvt_pk_f16_f32 v45, v50, v51
	global_store_dwordx4 v[54:55], v[42:45], off
	s_nop 0
	v_lshl_add_u64 v[46:47], v[164:165], 0, s[18:19]
	v_lshl_add_u64 v[48:49], v[46:47], 0, v[162:163]
	v_lshl_add_u64 v[50:51], v[62:63], 0, v[138:139]
	v_lshlrev_b64 v[48:49], 1, v[48:49]
	v_lshl_add_u64 v[50:51], v[50:51], 1, s[8:9]
	v_lshl_add_u64 v[52:53], s[82:83], 0, v[48:49]
	s_nop 0
	v_cvt_f32_f16_e32 v54, v228
	v_cvt_f32_f16_sdwa v55, v228 dst_sel:DWORD dst_unused:UNUSED_PAD src0_sel:WORD_1
	v_cvt_f32_f16_e32 v42, v229
	v_cvt_f32_f16_sdwa v43, v229 dst_sel:DWORD dst_unused:UNUSED_PAD src0_sel:WORD_1
	v_cvt_f32_f16_e32 v56, v230
	v_cvt_f32_f16_e32 v58, v231
	v_cvt_f32_f16_sdwa v59, v231 dst_sel:DWORD dst_unused:UNUSED_PAD src0_sel:WORD_1
	v_cvt_f32_f16_sdwa v57, v230 dst_sel:DWORD dst_unused:UNUSED_PAD src0_sel:WORD_1
	v_pk_fma_f32 v[40:41], v[40:41], v[128:129], v[42:43]
	v_pk_fma_f32 v[38:39], v[38:39], v[126:127], v[54:55]
	v_pk_fma_f32 v[42:43], v[36:37], v[124:125], v[58:59]
	v_pk_fma_f32 v[36:37], v[34:35], v[122:123], v[56:57]
	v_cvt_pk_f16_f32 v34, v38, v39
	v_cvt_pk_f16_f32 v35, v40, v41
	v_cvt_pk_f16_f32 v36, v36, v37
	v_cvt_pk_f16_f32 v37, v42, v43
	global_store_dwordx4 v[50:51], v[34:37], off
	s_nop 0
	v_lshl_add_u64 v[38:39], s[8:9], 0, v[48:49]
; __device__ __forceinline__ u32x4 packh44(const f32x4 a, const f32x4 b) { u32x4 w; w.x = pkh2(a[0], a[1]); w.y = pkh2(a[2], a[3]); w.z = pkh2(b[0], b[1]); w.w = pkh2(b[2], b[3]); return w; }
;     __device__ __forceinline__ bool operator()(f32x4 (&acc)[2][2][4][2], const Unit& u, int wr, int wc, int fr, int fq) const {
;     ...
;         EPI_LOOP_BEGIN const int col = u.pn * 256 + cl; const size_t off = (size_t)row * DM + col;
;             const f32x4 g0 = bj ? gb0 : ga0, g1 = bj ? gb1 : ga1; f32x4 x0, x1; unpackh44(*(const u32x4*)(base + off), x0, x1);
;             *(u32x4*)(o + off) = packh44(x0 + g0 * v0, x1 + g1 * v1); EPI_LOOP_END
	s_nop 0
	v_cvt_f32_f16_e32 v40, v236
	v_cvt_f32_f16_sdwa v41, v236 dst_sel:DWORD dst_unused:UNUSED_PAD src0_sel:WORD_1
	v_cvt_f32_f16_e32 v34, v237
	v_cvt_f32_f16_sdwa v35, v237 dst_sel:DWORD dst_unused:UNUSED_PAD src0_sel:WORD_1
	v_cvt_f32_f16_e32 v42, v238
	v_cvt_f32_f16_e32 v44, v239
	v_cvt_f32_f16_sdwa v45, v239 dst_sel:DWORD dst_unused:UNUSED_PAD src0_sel:WORD_1
	v_cvt_f32_f16_sdwa v43, v238 dst_sel:DWORD dst_unused:UNUSED_PAD src0_sel:WORD_1
	v_pk_fma_f32 v[32:33], v[32:33], v[136:137], v[34:35]
	v_pk_fma_f32 v[30:31], v[30:31], v[134:135], v[40:41]
	v_pk_fma_f32 v[34:35], v[28:29], v[132:133], v[44:45]
	v_pk_fma_f32 v[28:29], v[26:27], v[130:131], v[42:43]
	v_cvt_pk_f16_f32 v26, v30, v31
	v_cvt_pk_f16_f32 v27, v32, v33
	v_cvt_pk_f16_f32 v28, v28, v29
	v_cvt_pk_f16_f32 v29, v34, v35
	global_store_dwordx4 v[38:39], v[26:29], off
	s_nop 0
	v_lshl_add_u64 v[30:31], v[164:165], 0, s[20:21]
	v_lshl_add_u64 v[32:33], v[30:31], 0, v[162:163]
	v_lshl_add_u64 v[34:35], v[46:47], 0, v[138:139]
	v_lshlrev_b64 v[32:33], 1, v[32:33]
	v_lshl_add_u64 v[34:35], v[34:35], 1, s[8:9]
	v_lshl_add_u64 v[36:37], s[82:83], 0, v[32:33]
	s_nop 0
	v_cvt_f32_f16_e32 v38, v240
	v_cvt_f32_f16_sdwa v39, v240 dst_sel:DWORD dst_unused:UNUSED_PAD src0_sel:WORD_1
	v_cvt_f32_f16_e32 v26, v241
	v_cvt_f32_f16_sdwa v27, v241 dst_sel:DWORD dst_unused:UNUSED_PAD src0_sel:WORD_1
	v_cvt_f32_f16_e32 v40, v242
	v_cvt_f32_f16_e32 v42, v243
	v_cvt_f32_f16_sdwa v43, v243 dst_sel:DWORD dst_unused:UNUSED_PAD src0_sel:WORD_1
	v_cvt_f32_f16_sdwa v41, v242 dst_sel:DWORD dst_unused:UNUSED_PAD src0_sel:WORD_1
	v_pk_fma_f32 v[24:25], v[24:25], v[128:129], v[26:27]
	v_pk_fma_f32 v[22:23], v[22:23], v[126:127], v[38:39]
	v_pk_fma_f32 v[26:27], v[20:21], v[124:125], v[42:43]
	v_pk_fma_f32 v[20:21], v[18:19], v[122:123], v[40:41]
	v_cvt_pk_f16_f32 v18, v22, v23
	v_cvt_pk_f16_f32 v19, v24, v25
	v_cvt_pk_f16_f32 v20, v20, v21
	v_cvt_pk_f16_f32 v21, v26, v27
	global_store_dwordx4 v[34:35], v[18:21], off
	s_nop 0
	v_lshl_add_u64 v[22:23], s[8:9], 0, v[32:33]
	s_nop 0
	v_cvt_f32_f16_e32 v24, v244
	v_cvt_f32_f16_sdwa v25, v244 dst_sel:DWORD dst_unused:UNUSED_PAD src0_sel:WORD_1
	v_cvt_f32_f16_e32 v18, v245
	v_cvt_f32_f16_sdwa v19, v245 dst_sel:DWORD dst_unused:UNUSED_PAD src0_sel:WORD_1
	v_cvt_f32_f16_e32 v26, v246
	v_cvt_f32_f16_e32 v28, v247
	v_cvt_f32_f16_sdwa v29, v247 dst_sel:DWORD dst_unused:UNUSED_PAD src0_sel:WORD_1
	v_cvt_f32_f16_sdwa v27, v246 dst_sel:DWORD dst_unused:UNUSED_PAD src0_sel:WORD_1
	v_pk_fma_f32 v[16:17], v[16:17], v[136:137], v[18:19]
	v_pk_fma_f32 v[14:15], v[14:15], v[134:135], v[24:25]
	v_pk_fma_f32 v[18:19], v[12:13], v[132:133], v[28:29]
	v_pk_fma_f32 v[12:13], v[10:11], v[130:131], v[26:27]
	v_cvt_pk_f16_f32 v10, v14, v15
	v_cvt_pk_f16_f32 v11, v16, v17
	v_cvt_pk_f16_f32 v12, v12, v13
	v_cvt_pk_f16_f32 v13, v18, v19
	global_store_dwordx4 v[22:23], v[10:13], off
	s_nop 0
	v_lshl_add_u64 v[14:15], v[30:31], 0, v[138:139]
	v_lshl_add_u64 v[14:15], v[14:15], 1, s[8:9]
	s_nop 0
	v_cvt_f32_f16_e32 v16, v248
	v_cvt_f32_f16_sdwa v17, v248 dst_sel:DWORD dst_unused:UNUSED_PAD src0_sel:WORD_1
	v_cvt_f32_f16_e32 v10, v249
	v_cvt_f32_f16_sdwa v11, v249 dst_sel:DWORD dst_unused:UNUSED_PAD src0_sel:WORD_1
	v_cvt_f32_f16_e32 v18, v250
	v_cvt_f32_f16_e32 v20, v251
	v_cvt_f32_f16_sdwa v21, v251 dst_sel:DWORD dst_unused:UNUSED_PAD src0_sel:WORD_1
	v_cvt_f32_f16_sdwa v19, v250 dst_sel:DWORD dst_unused:UNUSED_PAD src0_sel:WORD_1
	v_pk_fma_f32 v[8:9], v[8:9], v[128:129], v[10:11]
	v_pk_fma_f32 v[6:7], v[6:7], v[126:127], v[16:17]
	v_pk_fma_f32 v[10:11], v[4:5], v[124:125], v[20:21]
	v_pk_fma_f32 v[4:5], v[2:3], v[122:123], v[18:19]
	v_cvt_pk_f16_f32 v2, v6, v7
	v_cvt_pk_f16_f32 v3, v8, v9
	v_cvt_pk_f16_f32 v4, v4, v5
	v_cvt_pk_f16_f32 v5, v10, v11
	global_store_dwordx4 v[14:15], v[2:5], off
	s_cbranch_vccnz .LBB0_932
	s_andn2_b64 vcc, exec, s[6:7]
	s_cbranch_vccnz .LBB0_931
	s_barrier
	s_branch .LBB0_931

; __global__ __launch_bounds__(512, 2) void mk_fwd(Params p) {
	.amdhsa_kernel _Z6mk_fwd6Params
		.amdhsa_group_segment_fixed_size 0
		.amdhsa_private_segment_fixed_size 0
		.amdhsa_kernarg_size 480
		.amdhsa_user_sgpr_count 2
		.amdhsa_user_sgpr_dispatch_ptr 0
		.amdhsa_user_sgpr_queue_ptr 0
		.amdhsa_user_sgpr_kernarg_segment_ptr 1
		.amdhsa_user_sgpr_dispatch_id 0
		.amdhsa_user_sgpr_kernarg_preload_length 0
		.amdhsa_user_sgpr_kernarg_preload_offset 0
		.amdhsa_user_sgpr_private_segment_size 0
		.amdhsa_uses_dynamic_stack 0
		.amdhsa_enable_private_segment 0
		.amdhsa_system_sgpr_workgroup_id_x 1
		.amdhsa_system_sgpr_workgroup_id_y 0
		.amdhsa_system_sgpr_workgroup_id_z 0
		.amdhsa_system_sgpr_workgroup_info 0
		.amdhsa_system_vgpr_workitem_id 2
		.amdhsa_next_free_vgpr 252
		.amdhsa_next_free_sgpr 98
		.amdhsa_accum_offset 252
		.amdhsa_reserve_vcc 1
		.amdhsa_float_round_mode_32 0
		.amdhsa_float_round_mode_16_64 0
		.amdhsa_float_denorm_mode_32 3
		.amdhsa_float_denorm_mode_16_64 3
		.amdhsa_dx10_clamp 1
		.amdhsa_ieee_mode 1
		.amdhsa_fp16_overflow 0
		.amdhsa_tg_split 0
		.amdhsa_exception_fp_ieee_invalid_op 0
		.amdhsa_exception_fp_denorm_src 0
		.amdhsa_exception_fp_ieee_div_zero 0
		.amdhsa_exception_fp_ieee_overflow 0
		.amdhsa_exception_fp_ieee_underflow 0
		.amdhsa_exception_fp_ieee_inexact 0
		.amdhsa_exception_int_div_zero 0
	.end_amdhsa_kernel

; __global__ __launch_bounds__(512, 2) void mk_fwd(Params p) {
amdhsa.kernels:
  - .agpr_count:     0
    .args:
      - .offset:         0
        .size:           224
        .value_kind:     by_value
      - .offset:         224
        .size:           4
        .value_kind:     hidden_block_count_x
      - .offset:         228
        .size:           4
        .value_kind:     hidden_block_count_y
      - .offset:         232
        .size:           4
        .value_kind:     hidden_block_count_z
      - .offset:         236
        .size:           2
        .value_kind:     hidden_group_size_x
      - .offset:         238
        .size:           2
        .value_kind:     hidden_group_size_y
      - .offset:         240
        .size:           2
        .value_kind:     hidden_group_size_z
      - .offset:         242
        .size:           2
        .value_kind:     hidden_remainder_x
      - .offset:         244
        .size:           2
        .value_kind:     hidden_remainder_y
      - .offset:         246
        .size:           2
        .value_kind:     hidden_remainder_z
      - .offset:         264
        .size:           8
        .value_kind:     hidden_global_offset_x
      - .offset:         272
        .size:           8
        .value_kind:     hidden_global_offset_y
      - .offset:         280
        .size:           8
        .value_kind:     hidden_global_offset_z
      - .offset:         288
        .size:           2
        .value_kind:     hidden_grid_dims
      - .offset:         312
        .size:           8
        .value_kind:     hidden_multigrid_sync_arg
      - .offset:         344
        .size:           4
        .value_kind:     hidden_dynamic_lds_size
    .group_segment_fixed_size: 0
    .kernarg_segment_align: 8
    .kernarg_segment_size: 480
    .language:       OpenCL C
    .language_version:
      - 2
      - 0
    .max_flat_workgroup_size: 512
    .name:           _Z6mk_fwd6Params
    .private_segment_fixed_size: 0
    .sgpr_count:     104
    .sgpr_spill_count: 94
    .symbol:         _Z6mk_fwd6Params.kd
    .uniform_work_group_size: 1
    .uses_dynamic_stack: false
    .vgpr_count:     252
    .vgpr_spill_count: 0
    .wavefront_size: 64
